# non-temporal hint also on the layer-1 f32 weight reads (converted by idle workgroups during layer 0)
# speedup vs baseline: 1.0567x; 1.0036x over previous
.LBB0_888:
	v_lshrrev_b32_e32 v52, 3, v1
	v_add_u32_e32 v1, v0, v52
	v_mad_i64_i32 v[4:5], s[8:9], s4, v1, 0
	v_cmp_lt_i32_e32 vcc, -1, v2
	v_lshl_add_u64 v[4:5], v[4:5], 2, s[6:7]
	v_mov_b32_e32 v8, 0
	v_cndmask_b32_e32 v2, 0, v2, vcc
	v_lshl_add_u64 v[38:39], v[2:3], 2, v[4:5]
	v_mov_b32_e32 v4, 0
	v_mov_b32_e32 v5, 0
	v_mov_b32_e32 v6, 0
	v_mov_b32_e32 v7, 0
	s_and_saveexec_b64 s[6:7], vcc
	s_cbranch_execz .LBB0_890
	global_load_dwordx4 v[4:7], v[38:39], off nt
.LBB0_890:
	s_or_b64 exec, exec, s[6:7]
	v_mov_b32_e32 v9, 0
	v_mov_b32_e32 v10, 0
	v_mov_b32_e32 v11, 0
	s_and_saveexec_b64 s[6:7], vcc
	s_cbranch_execz .LBB0_892
	s_lshl_b32 s92, s4, 5
	v_lshl_add_u64 v[8:9], v[38:39], 0, s[92:93]
	global_load_dwordx4 v[8:11], v[8:9], off nt
.LBB0_892:
	s_or_b64 exec, exec, s[6:7]
	v_mov_b32_e32 v12, 0
	v_mov_b32_e32 v16, 0
	v_mov_b32_e32 v17, 0
	v_mov_b32_e32 v18, 0
	v_mov_b32_e32 v19, 0
	s_and_saveexec_b64 s[6:7], vcc
	s_cbranch_execz .LBB0_894
	s_lshl_b32 s92, s4, 6
	v_lshl_add_u64 v[14:15], v[38:39], 0, s[92:93]
	global_load_dwordx4 v[16:19], v[14:15], off nt
.LBB0_894:
	s_or_b64 exec, exec, s[6:7]
	v_mov_b32_e32 v13, 0
	v_mov_b32_e32 v14, 0
	v_mov_b32_e32 v15, 0
	s_and_saveexec_b64 s[6:7], vcc
	s_cbranch_execz .LBB0_896
	s_mul_i32 s92, s4, 0x60
	v_lshl_add_u64 v[12:13], v[38:39], 0, s[92:93]
	global_load_dwordx4 v[12:15], v[12:13], off nt
.LBB0_896:
	s_or_b64 exec, exec, s[6:7]
	s_waitcnt vmcnt(3)
	v_mov_b32_e32 v20, 0
	s_waitcnt vmcnt(2)
	v_mov_b32_e32 v24, 0
	v_mov_b32_e32 v25, 0
	v_mov_b32_e32 v26, 0
	v_mov_b32_e32 v27, 0
	s_and_saveexec_b64 s[6:7], vcc
	s_cbranch_execz .LBB0_898
	s_lshl_b32 s92, s4, 7
	v_lshl_add_u64 v[22:23], v[38:39], 0, s[92:93]
	global_load_dwordx4 v[24:27], v[22:23], off nt
.LBB0_898:
	s_or_b64 exec, exec, s[6:7]
	v_mov_b32_e32 v21, 0
	v_mov_b32_e32 v22, 0
	v_mov_b32_e32 v23, 0
	s_and_saveexec_b64 s[6:7], vcc
	s_cbranch_execz .LBB0_900
	s_mul_i32 s92, s4, 0xa0
	v_lshl_add_u64 v[20:21], v[38:39], 0, s[92:93]
	global_load_dwordx4 v[20:23], v[20:21], off nt
.LBB0_900:
	s_or_b64 exec, exec, s[6:7]
	s_waitcnt vmcnt(1)
	v_mov_b32_e32 v28, 0
	s_waitcnt vmcnt(0)
	v_mov_b32_e32 v32, 0
	v_mov_b32_e32 v33, 0
	v_mov_b32_e32 v34, 0
	v_mov_b32_e32 v35, 0
	s_and_saveexec_b64 s[6:7], vcc
	s_cbranch_execz .LBB0_902
	s_mul_i32 s92, s4, 0xc0
	v_lshl_add_u64 v[30:31], v[38:39], 0, s[92:93]
	global_load_dwordx4 v[32:35], v[30:31], off nt
.LBB0_902:
	s_or_b64 exec, exec, s[6:7]
	v_mov_b32_e32 v29, 0
	v_mov_b32_e32 v30, 0
	v_mov_b32_e32 v31, 0
	s_and_saveexec_b64 s[6:7], vcc
	s_cbranch_execz .LBB0_904
	s_mul_i32 s92, s4, 0xe0
	v_lshl_add_u64 v[28:29], v[38:39], 0, s[92:93]
	global_load_dwordx4 v[28:31], v[28:29], off nt

.LBB0_935:
	v_add_u32_e32 v4, v46, v52
	v_mad_i64_i32 v[4:5], s[14:15], s8, v4, 0
	v_cmp_lt_i32_e32 vcc, -1, v2
	v_lshl_add_u64 v[4:5], v[4:5], 2, s[10:11]
	v_mov_b32_e32 v8, 0
	v_cndmask_b32_e32 v2, 0, v2, vcc
	v_lshl_add_u64 v[50:51], v[2:3], 2, v[4:5]
	v_mov_b32_e32 v4, 0
	v_mov_b32_e32 v5, 0
	v_mov_b32_e32 v6, 0
	v_mov_b32_e32 v7, 0
	s_and_saveexec_b64 s[10:11], vcc
	s_cbranch_execz .LBB0_937
	global_load_dwordx4 v[4:7], v[50:51], off nt
.LBB0_937:
	s_or_b64 exec, exec, s[10:11]
	v_mov_b32_e32 v9, 0
	v_mov_b32_e32 v10, 0
	v_mov_b32_e32 v11, 0
	s_and_saveexec_b64 s[10:11], vcc
	s_cbranch_execz .LBB0_939
	s_lshl_b32 s92, s8, 5
	v_lshl_add_u64 v[8:9], v[50:51], 0, s[92:93]
	global_load_dwordx4 v[8:11], v[8:9], off nt
.LBB0_939:
	s_or_b64 exec, exec, s[10:11]
	v_mov_b32_e32 v12, 0
	v_mov_b32_e32 v16, 0
	v_mov_b32_e32 v17, 0
	v_mov_b32_e32 v18, 0
	v_mov_b32_e32 v19, 0
	s_and_saveexec_b64 s[10:11], vcc
	s_cbranch_execz .LBB0_941
	s_lshl_b32 s92, s8, 6
	v_lshl_add_u64 v[14:15], v[50:51], 0, s[92:93]
	global_load_dwordx4 v[16:19], v[14:15], off nt
.LBB0_941:
	s_or_b64 exec, exec, s[10:11]
	v_mov_b32_e32 v13, 0
	v_mov_b32_e32 v14, 0
	v_mov_b32_e32 v15, 0
	s_and_saveexec_b64 s[10:11], vcc
	s_cbranch_execz .LBB0_943
	v_mov_b32_e32 v2, 0x60
	v_mad_u64_u32 v[12:13], s[14:15], s8, v2, v[50:51]
	global_load_dwordx4 v[12:15], v[12:13], off nt
.LBB0_943:
	s_or_b64 exec, exec, s[10:11]
	v_mov_b32_e32 v20, 0
	v_mov_b32_e32 v24, 0
	v_mov_b32_e32 v25, 0
	v_mov_b32_e32 v26, 0
	v_mov_b32_e32 v27, 0
	s_and_saveexec_b64 s[10:11], vcc
	s_cbranch_execz .LBB0_945
	s_lshl_b32 s92, s8, 7
	v_lshl_add_u64 v[22:23], v[50:51], 0, s[92:93]
	global_load_dwordx4 v[24:27], v[22:23], off nt
.LBB0_945:
	s_or_b64 exec, exec, s[10:11]
	v_mov_b32_e32 v21, 0
	v_mov_b32_e32 v22, 0
	v_mov_b32_e32 v23, 0
	s_and_saveexec_b64 s[10:11], vcc
	s_cbranch_execz .LBB0_947
	v_mov_b32_e32 v2, 0xa0
	v_mad_u64_u32 v[20:21], s[14:15], s8, v2, v[50:51]
	global_load_dwordx4 v[20:23], v[20:21], off nt
.LBB0_947:
	s_or_b64 exec, exec, s[10:11]
	v_mov_b32_e32 v28, 0
	v_mov_b32_e32 v32, 0
	v_mov_b32_e32 v33, 0
	v_mov_b32_e32 v34, 0
	v_mov_b32_e32 v35, 0
	s_and_saveexec_b64 s[10:11], vcc
	s_cbranch_execz .LBB0_949
	v_mov_b32_e32 v2, 0xc0
	v_mad_u64_u32 v[30:31], s[14:15], s8, v2, v[50:51]
	global_load_dwordx4 v[32:35], v[30:31], off nt
.LBB0_949:
	s_or_b64 exec, exec, s[10:11]
	v_mov_b32_e32 v29, 0
	v_mov_b32_e32 v30, 0
	v_mov_b32_e32 v31, 0
	s_and_saveexec_b64 s[10:11], vcc
	s_cbranch_execz .LBB0_905
	v_mad_u64_u32 v[28:29], s[8:9], s8, v241, v[50:51]
	global_load_dwordx4 v[28:31], v[28:29], off nt
	s_branch .LBB0_905
